# PEER top-k: insertion of 64 / 16 values into the sorted top-16 list replaced by sorting/merging networks (same unique result), on top of v11
# speedup vs baseline: 1.0085x; 1.0077x over previous
; #define MFMA(a, b, c) __builtin_amdgcn_mfma_f32_16x16x32_bf16((a), (b), (c), 0, 0, 0)
; #define P (*launderP(lp))
; __device__ __forceinline__ void peer_topk_item(PREF P, int w, char* smem) {
;     ...
;   __syncthreads();
;   {
;     const int c = wid >> 1, th = wid & 1;
;     f32x4 acc[8][2];
; #pragma unroll
;     for (int a = 0; a < 8; ++a) { acc[a][0] = f32x4{0.f, 0.f, 0.f, 0.f}; acc[a][1] = f32x4{0.f, 0.f, 0.f, 0.f}; }
; #pragma unroll
;     for (int kd = 0; kd < 4; ++kd) {
;       bf16x8 qf[2];
; #pragma unroll
;       for (int tt = 0; tt < 2; ++tt)
;         qf[tt] = *(const bf16x8*)(P.qb + (size_t)(t0 + th * 32 + tt * 16 + l15) * 2048 + h * 256 + c * 128 + kd * 32 + q * 8);
; #pragma unroll
;       for (int kt = 0; kt < 8; ++kt) {
;         bf16x8 kf = *(const bf16x8*)(P.keysb + (size_t)((h * 2 + c) * 128 + kt * 16 + l15) * 128 + kd * 32 + q * 8);
;         acc[kt][0] = MFMA(kf, qf[0], acc[kt][0]);
;         acc[kt][1] = MFMA(kf, qf[1], acc[kt][1]);
;       }
;     }
.LBB0_627:
	v_mov_b32_e32 v52, 0x12400
	v_mov_b32_e32 v53, v188
	s_barrier
	ds_read2_b64 v[0:3], v52 offset0:25 offset1:44
	s_and_b32 s15, s14, 7
	s_lshl_b32 s24, s15, 9
	v_and_b32_e32 v6, 0xffffff80, v53
	s_lshl_b32 s16, s14, 3
	v_lshrrev_b32_e32 v56, 1, v53
	s_waitcnt lgkmcnt(0)
	v_lshl_add_u64 v[2:3], v[2:3], 0, s[24:25]
	v_ashrrev_i32_e32 v7, 31, v6
	v_and_b32_e32 v54, 15, v53
	s_andn2_b32 s16, s16, 63
	v_and_b32_e32 v55, 32, v56
	v_lshl_add_u64 v[2:3], v[6:7], 1, v[2:3]
	v_and_b32_e32 v180, 48, v53
	v_or3_b32 v4, v55, v54, s16
	v_lshl_add_u64 v[8:9], v[2:3], 0, v[180:181]
	v_lshl_add_u32 v2, s15, 8, v6
	v_or_b32_e32 v12, v2, v54
	v_ashrrev_i32_e32 v5, 31, v4
	v_lshl_add_u64 v[14:15], v[0:1], 0, v[180:181]
	v_ashrrev_i32_e32 v13, 31, v12
	v_lshlrev_b64 v[0:1], 12, v[4:5]
	v_or_b32_e32 v4, 16, v4
	v_lshlrev_b64 v[10:11], 8, v[12:13]
	v_ashrrev_i32_e32 v5, 31, v4
	v_lshlrev_b64 v[4:5], 12, v[4:5]
	v_lshl_add_u64 v[44:45], v[14:15], 0, v[10:11]
	v_lshl_add_u64 v[48:49], v[8:9], 0, v[0:1]
	v_lshl_add_u64 v[50:51], v[8:9], 0, v[4:5]
	flat_load_dwordx4 v[8:11], v[44:45]
	flat_load_dwordx4 v[0:3], v[48:49]
	flat_load_dwordx4 v[4:7], v[50:51]
	s_movk_i32 s6, 0x204
	s_waitcnt vmcnt(0) lgkmcnt(0)
	v_mfma_f32_16x16x32_bf16 v[58:61], v[8:11], v[0:3], 0
	v_mfma_f32_16x16x32_bf16 v[62:65], v[8:11], v[4:7], 0
	v_or_b32_e32 v8, 16, v12
	v_ashrrev_i32_e32 v9, 31, v8
	v_lshlrev_b64 v[8:9], 8, v[8:9]
	v_lshl_add_u64 v[46:47], v[14:15], 0, v[8:9]
	flat_load_dwordx4 v[8:11], v[46:47]
	s_waitcnt vmcnt(0) lgkmcnt(0)
	v_mfma_f32_16x16x32_bf16 v[66:69], v[8:11], v[0:3], 0
	v_mfma_f32_16x16x32_bf16 v[70:73], v[8:11], v[4:7], 0
	v_or_b32_e32 v8, 32, v12
	v_ashrrev_i32_e32 v9, 31, v8
	v_lshlrev_b64 v[8:9], 8, v[8:9]
	v_lshl_add_u64 v[42:43], v[14:15], 0, v[8:9]
	flat_load_dwordx4 v[8:11], v[42:43]
	s_waitcnt vmcnt(0) lgkmcnt(0)
	v_mfma_f32_16x16x32_bf16 v[74:77], v[8:11], v[0:3], 0
	v_mfma_f32_16x16x32_bf16 v[78:81], v[8:11], v[4:7], 0
	v_or_b32_e32 v8, 48, v12
	v_ashrrev_i32_e32 v9, 31, v8
	v_lshlrev_b64 v[8:9], 8, v[8:9]
	v_lshl_add_u64 v[40:41], v[14:15], 0, v[8:9]
	flat_load_dwordx4 v[8:11], v[40:41]
	s_waitcnt vmcnt(0) lgkmcnt(0)
	v_mfma_f32_16x16x32_bf16 v[82:85], v[8:11], v[0:3], 0
	v_mfma_f32_16x16x32_bf16 v[86:89], v[8:11], v[4:7], 0
	v_or_b32_e32 v8, 64, v12
	v_ashrrev_i32_e32 v9, 31, v8
	v_lshlrev_b64 v[8:9], 8, v[8:9]
	v_lshl_add_u64 v[38:39], v[14:15], 0, v[8:9]
	flat_load_dwordx4 v[8:11], v[38:39]
	s_waitcnt vmcnt(0) lgkmcnt(0)
	v_mfma_f32_16x16x32_bf16 v[90:93], v[8:11], v[0:3], 0
	v_mfma_f32_16x16x32_bf16 v[94:97], v[8:11], v[4:7], 0
	v_or_b32_e32 v8, 0x50, v12
	v_ashrrev_i32_e32 v9, 31, v8
	v_lshlrev_b64 v[8:9], 8, v[8:9]
	v_lshl_add_u64 v[36:37], v[14:15], 0, v[8:9]
	flat_load_dwordx4 v[8:11], v[36:37]
	s_waitcnt vmcnt(0) lgkmcnt(0)
	v_mfma_f32_16x16x32_bf16 v[24:27], v[8:11], v[0:3], 0
	v_mfma_f32_16x16x32_bf16 v[28:31], v[8:11], v[4:7], 0
	v_or_b32_e32 v8, 0x60, v12
	v_ashrrev_i32_e32 v9, 31, v8
	v_lshlrev_b64 v[8:9], 8, v[8:9]
	v_lshl_add_u64 v[34:35], v[14:15], 0, v[8:9]
	flat_load_dwordx4 v[8:11], v[34:35]
	s_waitcnt vmcnt(0) lgkmcnt(0)
	v_mfma_f32_16x16x32_bf16 v[16:19], v[8:11], v[0:3], 0
	v_mfma_f32_16x16x32_bf16 v[20:23], v[8:11], v[4:7], 0
	v_or_b32_e32 v8, 0x70, v12
	v_ashrrev_i32_e32 v9, 31, v8
	v_lshlrev_b64 v[8:9], 8, v[8:9]
	v_lshl_add_u64 v[32:33], v[14:15], 0, v[8:9]
	flat_load_dwordx4 v[8:11], v[32:33]
	s_waitcnt vmcnt(0) lgkmcnt(0)
	v_mfma_f32_16x16x32_bf16 v[0:3], v[8:11], v[0:3], 0
	v_mfma_f32_16x16x32_bf16 v[4:7], v[8:11], v[4:7], 0
	flat_load_dwordx4 v[8:11], v[48:49] offset:64
	flat_load_dwordx4 v[12:15], v[50:51] offset:64
	flat_load_dwordx4 v[98:101], v[44:45] offset:64
	s_waitcnt vmcnt(0) lgkmcnt(0)
	v_mfma_f32_16x16x32_bf16 v[58:61], v[98:101], v[8:11], v[58:61]
	v_mfma_f32_16x16x32_bf16 v[62:65], v[98:101], v[12:15], v[62:65]
	flat_load_dwordx4 v[98:101], v[46:47] offset:64
	s_waitcnt vmcnt(0) lgkmcnt(0)
	v_mfma_f32_16x16x32_bf16 v[66:69], v[98:101], v[8:11], v[66:69]
	v_mfma_f32_16x16x32_bf16 v[70:73], v[98:101], v[12:15], v[70:73]
	flat_load_dwordx4 v[98:101], v[42:43] offset:64
	s_waitcnt vmcnt(0) lgkmcnt(0)
	v_mfma_f32_16x16x32_bf16 v[74:77], v[98:101], v[8:11], v[74:77]
	v_mfma_f32_16x16x32_bf16 v[78:81], v[98:101], v[12:15], v[78:81]
	flat_load_dwordx4 v[98:101], v[40:41] offset:64
	s_waitcnt vmcnt(0) lgkmcnt(0)
	v_mfma_f32_16x16x32_bf16 v[82:85], v[98:101], v[8:11], v[82:85]
	v_mfma_f32_16x16x32_bf16 v[86:89], v[98:101], v[12:15], v[86:89]
	flat_load_dwordx4 v[98:101], v[38:39] offset:64
	s_waitcnt vmcnt(0) lgkmcnt(0)
	v_mfma_f32_16x16x32_bf16 v[90:93], v[98:101], v[8:11], v[90:93]
	v_mfma_f32_16x16x32_bf16 v[94:97], v[98:101], v[12:15], v[94:97]
	flat_load_dwordx4 v[98:101], v[36:37] offset:64
	s_waitcnt vmcnt(0) lgkmcnt(0)
	v_mfma_f32_16x16x32_bf16 v[24:27], v[98:101], v[8:11], v[24:27]
	v_mfma_f32_16x16x32_bf16 v[28:31], v[98:101], v[12:15], v[28:31]
	flat_load_dwordx4 v[98:101], v[34:35] offset:64
	s_waitcnt vmcnt(0) lgkmcnt(0)
	v_mfma_f32_16x16x32_bf16 v[16:19], v[98:101], v[8:11], v[16:19]
	v_mfma_f32_16x16x32_bf16 v[20:23], v[98:101], v[12:15], v[20:23]
	flat_load_dwordx4 v[98:101], v[32:33] offset:64
	s_waitcnt vmcnt(0) lgkmcnt(0)
	v_mfma_f32_16x16x32_bf16 v[0:3], v[98:101], v[8:11], v[0:3]
	v_mfma_f32_16x16x32_bf16 v[4:7], v[98:101], v[12:15], v[4:7]
	flat_load_dwordx4 v[8:11], v[48:49] offset:128
	flat_load_dwordx4 v[12:15], v[50:51] offset:128
	flat_load_dwordx4 v[98:101], v[44:45] offset:128
	s_waitcnt vmcnt(0) lgkmcnt(0)
	v_mfma_f32_16x16x32_bf16 v[58:61], v[98:101], v[8:11], v[58:61]
	v_mfma_f32_16x16x32_bf16 v[62:65], v[98:101], v[12:15], v[62:65]
	flat_load_dwordx4 v[98:101], v[46:47] offset:128
	s_waitcnt vmcnt(0) lgkmcnt(0)
; #define MFMA(a, b, c) __builtin_amdgcn_mfma_f32_16x16x32_bf16((a), (b), (c), 0, 0, 0)
; __device__ __forceinline__ void peer_topk_item(PREF P, int w, char* smem) {
;     ...
;         acc[kt][0] = MFMA(kf, qf[0], acc[kt][0]);
;         acc[kt][1] = MFMA(kf, qf[1], acc[kt][1]);
;       }
;     }
; #pragma unroll
;     for (int kt = 0; kt < 8; ++kt)
; #pragma unroll
;       for (int tt = 0; tt < 2; ++tt)
; #pragma unroll
;         for (int r = 0; r < 4; ++r) Ls[(c * 64 + th * 32 + tt * 16 + l15) * 129 + kt * 16 + q * 4 + r] = acc[kt][tt][r];
;   }
;   __syncthreads();
;   {
;     const int row = tid & 127, half = tid >> 7;
;     float top[16];
; #pragma unroll
;     for (int k = 0; k < 16; ++k) top[k] = -3.0e38f;
	v_mfma_f32_16x16x32_bf16 v[66:69], v[98:101], v[8:11], v[66:69]
	v_mfma_f32_16x16x32_bf16 v[70:73], v[98:101], v[12:15], v[70:73]
	flat_load_dwordx4 v[98:101], v[42:43] offset:128
	s_waitcnt vmcnt(0) lgkmcnt(0)
	v_mfma_f32_16x16x32_bf16 v[74:77], v[98:101], v[8:11], v[74:77]
	v_mfma_f32_16x16x32_bf16 v[78:81], v[98:101], v[12:15], v[78:81]
	flat_load_dwordx4 v[98:101], v[40:41] offset:128
	s_waitcnt vmcnt(0) lgkmcnt(0)
	v_mfma_f32_16x16x32_bf16 v[82:85], v[98:101], v[8:11], v[82:85]
	v_mfma_f32_16x16x32_bf16 v[86:89], v[98:101], v[12:15], v[86:89]
	flat_load_dwordx4 v[98:101], v[38:39] offset:128
	s_waitcnt vmcnt(0) lgkmcnt(0)
	v_mfma_f32_16x16x32_bf16 v[90:93], v[98:101], v[8:11], v[90:93]
	v_mfma_f32_16x16x32_bf16 v[94:97], v[98:101], v[12:15], v[94:97]
	flat_load_dwordx4 v[98:101], v[36:37] offset:128
	s_waitcnt vmcnt(0) lgkmcnt(0)
	v_mfma_f32_16x16x32_bf16 v[24:27], v[98:101], v[8:11], v[24:27]
	v_mfma_f32_16x16x32_bf16 v[28:31], v[98:101], v[12:15], v[28:31]
	flat_load_dwordx4 v[98:101], v[34:35] offset:128
	s_waitcnt vmcnt(0) lgkmcnt(0)
	v_mfma_f32_16x16x32_bf16 v[16:19], v[98:101], v[8:11], v[16:19]
	v_mfma_f32_16x16x32_bf16 v[20:23], v[98:101], v[12:15], v[20:23]
	flat_load_dwordx4 v[98:101], v[32:33] offset:128
	s_waitcnt vmcnt(0) lgkmcnt(0)
	v_mfma_f32_16x16x32_bf16 v[0:3], v[98:101], v[8:11], v[0:3]
	v_mfma_f32_16x16x32_bf16 v[4:7], v[98:101], v[12:15], v[4:7]
	flat_load_dwordx4 v[8:11], v[48:49] offset:192
	flat_load_dwordx4 v[12:15], v[50:51] offset:192
	s_nop 0
	flat_load_dwordx4 v[48:51], v[44:45] offset:192
	s_nop 0
	flat_load_dwordx4 v[44:47], v[46:47] offset:192
	s_waitcnt vmcnt(0) lgkmcnt(0)
	v_mfma_f32_16x16x32_bf16 v[58:61], v[48:51], v[8:11], v[58:61]
	v_mfma_f32_16x16x32_bf16 v[48:51], v[48:51], v[12:15], v[62:65]
	v_mfma_f32_16x16x32_bf16 v[62:65], v[44:47], v[8:11], v[66:69]
	s_nop 2
	flat_load_dwordx4 v[66:69], v[42:43] offset:192
	v_mfma_f32_16x16x32_bf16 v[44:47], v[44:47], v[12:15], v[70:73]
	flat_load_dwordx4 v[40:43], v[40:41] offset:192
	s_waitcnt vmcnt(0) lgkmcnt(0)
	v_mfma_f32_16x16x32_bf16 v[70:73], v[66:69], v[8:11], v[74:77]
	v_mfma_f32_16x16x32_bf16 v[66:69], v[66:69], v[12:15], v[78:81]
	s_nop 2
	flat_load_dwordx4 v[78:81], v[38:39] offset:192
	s_nop 0
	flat_load_dwordx4 v[36:39], v[36:37] offset:192
	s_waitcnt vmcnt(0) lgkmcnt(0)
	v_mfma_f32_16x16x32_bf16 v[24:27], v[36:39], v[8:11], v[24:27]
	v_mfma_f32_16x16x32_bf16 v[28:31], v[36:39], v[12:15], v[28:31]
	flat_load_dwordx4 v[34:37], v[34:35] offset:192
	s_waitcnt vmcnt(0) lgkmcnt(0)
	v_mfma_f32_16x16x32_bf16 v[16:19], v[34:37], v[8:11], v[16:19]
	v_mfma_f32_16x16x32_bf16 v[20:23], v[34:37], v[12:15], v[20:23]
	flat_load_dwordx4 v[32:35], v[32:33] offset:192
	v_mfma_f32_16x16x32_bf16 v[74:77], v[40:43], v[8:11], v[82:85]
	v_mfma_f32_16x16x32_bf16 v[82:85], v[78:81], v[8:11], v[90:93]
	s_waitcnt vmcnt(0) lgkmcnt(0)
	v_mfma_f32_16x16x32_bf16 v[0:3], v[32:35], v[8:11], v[0:3]
	v_and_b32_e32 v8, 0x3fffffc0, v56
	v_or3_b32 v8, v54, v8, v55
	v_mad_u64_u32 v[8:9], s[4:5], v8, s6, v[180:181]
	v_add_u32_e32 v9, 0x2040, v8
	ds_write2_b32 v8, v58, v59 offset1:1
	ds_write2_b32 v8, v60, v61 offset0:2 offset1:3
	ds_write2_b32 v9, v48, v49 offset1:1
	v_add_u32_e32 v9, 0x2048, v8
	ds_write2_b32 v9, v50, v51 offset1:1
	ds_write2_b32 v8, v62, v63 offset0:16 offset1:17
	ds_write2_b32 v8, v64, v65 offset0:18 offset1:19
	v_add_u32_e32 v9, 0x2080, v8
	v_mfma_f32_16x16x32_bf16 v[40:43], v[40:43], v[12:15], v[86:89]
	ds_write2_b32 v9, v44, v45 offset1:1
	v_add_u32_e32 v9, 0x2088, v8
	ds_write2_b32 v9, v46, v47 offset1:1
	ds_write2_b32 v8, v70, v71 offset0:32 offset1:33
	ds_write2_b32 v8, v72, v73 offset0:34 offset1:35
	v_add_u32_e32 v9, 0x20c0, v8
	v_mfma_f32_16x16x32_bf16 v[78:81], v[78:81], v[12:15], v[94:97]
	ds_write2_b32 v9, v66, v67 offset1:1
	v_add_u32_e32 v9, 0x20c8, v8
	ds_write2_b32 v9, v68, v69 offset1:1
	ds_write2_b32 v8, v74, v75 offset0:48 offset1:49
	ds_write2_b32 v8, v76, v77 offset0:50 offset1:51
	v_add_u32_e32 v9, 0x2100, v8
	ds_write2_b32 v9, v40, v41 offset1:1
	v_add_u32_e32 v9, 0x2108, v8
	ds_write2_b32 v9, v42, v43 offset1:1
	ds_write2_b32 v8, v82, v83 offset0:64 offset1:65
	ds_write2_b32 v8, v84, v85 offset0:66 offset1:67
	v_add_u32_e32 v9, 0x2140, v8
	ds_write2_b32 v9, v78, v79 offset1:1
	v_add_u32_e32 v9, 0x2148, v8
	ds_write2_b32 v9, v80, v81 offset1:1
	ds_write2_b32 v8, v24, v25 offset0:80 offset1:81
	ds_write2_b32 v8, v26, v27 offset0:82 offset1:83
	v_add_u32_e32 v9, 0x2180, v8
	v_mfma_f32_16x16x32_bf16 v[4:7], v[32:35], v[12:15], v[4:7]
	ds_write2_b32 v9, v28, v29 offset1:1
	v_add_u32_e32 v9, 0x2188, v8
	ds_write2_b32 v9, v30, v31 offset1:1
	ds_write2_b32 v8, v16, v17 offset0:96 offset1:97
	ds_write2_b32 v8, v18, v19 offset0:98 offset1:99
	v_add_u32_e32 v9, 0x21c0, v8
	ds_write2_b32 v9, v20, v21 offset1:1
	v_add_u32_e32 v9, 0x21c8, v8
	ds_write2_b32 v9, v22, v23 offset1:1
	ds_write2_b32 v8, v0, v1 offset0:112 offset1:113
	ds_write2_b32 v8, v2, v3 offset0:114 offset1:115
	v_add_u32_e32 v0, 0x2200, v8
	ds_write2_b32 v0, v4, v5 offset1:1
	v_add_u32_e32 v0, 0x2208, v8
	v_ashrrev_i32_e32 v1, 7, v53
	ds_write2_b32 v0, v6, v7 offset1:1
	v_and_b32_e32 v0, 0x7f, v53
	v_lshlrev_b32_e32 v3, 8, v1
	v_lshlrev_b32_e32 v2, 6, v1
	v_mad_u32_u24 v3, v0, s6, v3
	v_mov_b32_e32 v19, 0xff61b1e6
	s_mov_b32 s4, 0
	v_mov_b32_e32 v18, 0xff61b1e6
	v_mov_b32_e32 v17, 0xff61b1e6
	v_mov_b32_e32 v16, 0xff61b1e6
	v_mov_b32_e32 v15, 0xff61b1e6
	v_mov_b32_e32 v14, 0xff61b1e6
	v_mov_b32_e32 v13, 0xff61b1e6
	v_mov_b32_e32 v12, 0xff61b1e6
	v_mov_b32_e32 v11, 0xff61b1e6
	v_mov_b32_e32 v10, 0xff61b1e6
	v_mov_b32_e32 v9, 0xff61b1e6
	v_mov_b32_e32 v8, 0xff61b1e6
	v_mov_b32_e32 v7, 0xff61b1e6
	v_mov_b32_e32 v6, 0xff61b1e6
	v_mov_b32_e32 v5, 0xff61b1e6
	v_mov_b32_e32 v4, 0xff61b1e6
	s_waitcnt lgkmcnt(0)
	s_barrier
; __device__ __forceinline__ void peer_topk_item(PREF P, int w, char* smem) {
;     ...
;     const float* src = Ls + row * 129 + half * 64;
; #pragma unroll 4
;     for (int k = 0; k < 64; ++k) {
;       float x = __uint_as_float((__float_as_uint(src[k]) & ~127u) | (unsigned)(half * 64 + k));
;       ce_insert(top, x);
	ds_read2_b32 v[66:67], v3 offset0:0 offset1:1
	ds_read2_b32 v[68:69], v3 offset0:2 offset1:3
	ds_read2_b32 v[70:71], v3 offset0:4 offset1:5
	ds_read2_b32 v[72:73], v3 offset0:6 offset1:7
	ds_read2_b32 v[74:75], v3 offset0:8 offset1:9
	ds_read2_b32 v[76:77], v3 offset0:10 offset1:11
	ds_read2_b32 v[78:79], v3 offset0:12 offset1:13
	ds_read2_b32 v[80:81], v3 offset0:14 offset1:15
	ds_read2_b32 v[82:83], v3 offset0:16 offset1:17
	ds_read2_b32 v[84:85], v3 offset0:18 offset1:19
	ds_read2_b32 v[86:87], v3 offset0:20 offset1:21
	ds_read2_b32 v[88:89], v3 offset0:22 offset1:23
	ds_read2_b32 v[90:91], v3 offset0:24 offset1:25
	ds_read2_b32 v[92:93], v3 offset0:26 offset1:27
	ds_read2_b32 v[94:95], v3 offset0:28 offset1:29
	ds_read2_b32 v[96:97], v3 offset0:30 offset1:31
	s_waitcnt lgkmcnt(8)
	v_and_b32_e32 v66, 0xffffff80, v66
	v_and_b32_e32 v67, 0xffffff80, v67
	v_and_b32_e32 v68, 0xffffff80, v68
	v_and_b32_e32 v69, 0xffffff80, v69
	v_and_b32_e32 v70, 0xffffff80, v70
	v_and_b32_e32 v71, 0xffffff80, v71
	v_and_b32_e32 v72, 0xffffff80, v72
	v_and_b32_e32 v73, 0xffffff80, v73
	v_and_b32_e32 v74, 0xffffff80, v74
	v_and_b32_e32 v75, 0xffffff80, v75
	v_and_b32_e32 v76, 0xffffff80, v76
	v_and_b32_e32 v77, 0xffffff80, v77
	v_and_b32_e32 v78, 0xffffff80, v78
	v_and_b32_e32 v79, 0xffffff80, v79
	v_and_b32_e32 v80, 0xffffff80, v80
	v_and_b32_e32 v81, 0xffffff80, v81
	ds_read2_b32 v[98:99], v3 offset0:32 offset1:33
	ds_read2_b32 v[100:101], v3 offset0:34 offset1:35
	ds_read2_b32 v[102:103], v3 offset0:36 offset1:37
	ds_read2_b32 v[104:105], v3 offset0:38 offset1:39
	ds_read2_b32 v[106:107], v3 offset0:40 offset1:41
	ds_read2_b32 v[108:109], v3 offset0:42 offset1:43
	ds_read2_b32 v[110:111], v3 offset0:44 offset1:45
	ds_read2_b32 v[112:113], v3 offset0:46 offset1:47
	v_or3_b32 v66, v2, v66, 0
	v_or3_b32 v67, v2, v67, 1
	v_or3_b32 v68, v2, v68, 2
	v_or3_b32 v69, v2, v69, 3
	v_or3_b32 v70, v2, v70, 4
	v_or3_b32 v71, v2, v71, 5
	v_or3_b32 v72, v2, v72, 6
	v_or3_b32 v73, v2, v73, 7
	v_or3_b32 v74, v2, v74, 8
	v_or3_b32 v75, v2, v75, 9
	v_or3_b32 v76, v2, v76, 10
	v_or3_b32 v77, v2, v77, 11
	v_or3_b32 v78, v2, v78, 12
	v_or3_b32 v79, v2, v79, 13
	v_or3_b32 v80, v2, v80, 14
	v_or3_b32 v81, v2, v81, 15
	s_waitcnt lgkmcnt(8)
	v_and_b32_e32 v82, 0xffffff80, v82
	v_and_b32_e32 v83, 0xffffff80, v83
	v_and_b32_e32 v84, 0xffffff80, v84
	v_and_b32_e32 v85, 0xffffff80, v85
	v_and_b32_e32 v86, 0xffffff80, v86
	v_and_b32_e32 v87, 0xffffff80, v87
	v_and_b32_e32 v88, 0xffffff80, v88
	v_and_b32_e32 v89, 0xffffff80, v89
	v_and_b32_e32 v90, 0xffffff80, v90
	v_and_b32_e32 v91, 0xffffff80, v91
	v_and_b32_e32 v92, 0xffffff80, v92
	v_and_b32_e32 v93, 0xffffff80, v93
	v_and_b32_e32 v94, 0xffffff80, v94
	v_and_b32_e32 v95, 0xffffff80, v95
	v_and_b32_e32 v96, 0xffffff80, v96
	v_and_b32_e32 v97, 0xffffff80, v97
	ds_read2_b32 v[114:115], v3 offset0:48 offset1:49
	ds_read2_b32 v[116:117], v3 offset0:50 offset1:51
	ds_read2_b32 v[118:119], v3 offset0:52 offset1:53
	ds_read2_b32 v[120:121], v3 offset0:54 offset1:55
	ds_read2_b32 v[122:123], v3 offset0:56 offset1:57
	ds_read2_b32 v[124:125], v3 offset0:58 offset1:59
	ds_read2_b32 v[126:127], v3 offset0:60 offset1:61
	ds_read2_b32 v[128:129], v3 offset0:62 offset1:63
	v_or3_b32 v82, v2, v82, 16
	v_or3_b32 v83, v2, v83, 17
	v_or3_b32 v84, v2, v84, 18
	v_or3_b32 v85, v2, v85, 19
	v_or3_b32 v86, v2, v86, 20
	v_or3_b32 v87, v2, v87, 21
	v_or3_b32 v88, v2, v88, 22
	v_or3_b32 v89, v2, v89, 23
	v_or3_b32 v90, v2, v90, 24
	v_or3_b32 v91, v2, v91, 25
	v_or3_b32 v92, v2, v92, 26
	v_or3_b32 v93, v2, v93, 27
	v_or3_b32 v94, v2, v94, 28
	v_or3_b32 v95, v2, v95, 29
	v_or3_b32 v96, v2, v96, 30
	v_or3_b32 v97, v2, v97, 31
	s_waitcnt lgkmcnt(8)
	v_and_b32_e32 v98, 0xffffff80, v98
	v_and_b32_e32 v99, 0xffffff80, v99
	v_and_b32_e32 v100, 0xffffff80, v100
	v_and_b32_e32 v101, 0xffffff80, v101
	v_and_b32_e32 v102, 0xffffff80, v102
	v_and_b32_e32 v103, 0xffffff80, v103
	v_and_b32_e32 v104, 0xffffff80, v104
	v_and_b32_e32 v105, 0xffffff80, v105
	v_and_b32_e32 v106, 0xffffff80, v106
	v_and_b32_e32 v107, 0xffffff80, v107
	v_and_b32_e32 v108, 0xffffff80, v108
	v_and_b32_e32 v109, 0xffffff80, v109
	v_and_b32_e32 v110, 0xffffff80, v110
	v_and_b32_e32 v111, 0xffffff80, v111
	v_and_b32_e32 v112, 0xffffff80, v112
	v_and_b32_e32 v113, 0xffffff80, v113
	v_or3_b32 v98, v2, v98, 32
	v_or3_b32 v99, v2, v99, 33
	v_or3_b32 v100, v2, v100, 34
	v_or3_b32 v101, v2, v101, 35
	v_or3_b32 v102, v2, v102, 36
	v_or3_b32 v103, v2, v103, 37
	v_or3_b32 v104, v2, v104, 38
	v_or3_b32 v105, v2, v105, 39
	v_or3_b32 v106, v2, v106, 40
	v_or3_b32 v107, v2, v107, 41
	v_or3_b32 v108, v2, v108, 42
	v_or3_b32 v109, v2, v109, 43
	v_or3_b32 v110, v2, v110, 44
	v_or3_b32 v111, v2, v111, 45
	v_or3_b32 v112, v2, v112, 46
	v_or3_b32 v113, v2, v113, 47
	s_waitcnt lgkmcnt(0)
; DEV void ce_insert(float (&top)[16], float x) {
; #pragma unroll
;   for (int p = 0; p < 16; ++p) {
;     float hi = fmaxf(top[p], x), lo = fminf(top[p], x);
;     top[p] = hi; x = lo;
;   }
; }
; __device__ __forceinline__ void peer_topk_item(PREF P, int w, char* smem) {
;     ...
; #pragma unroll 4
;     for (int k = 0; k < 64; ++k) {
;       float x = __uint_as_float((__float_as_uint(src[k]) & ~127u) | (unsigned)(half * 64 + k));
;       ce_insert(top, x);
	v_and_b32_e32 v114, 0xffffff80, v114
	v_and_b32_e32 v115, 0xffffff80, v115
	v_and_b32_e32 v116, 0xffffff80, v116
	v_and_b32_e32 v117, 0xffffff80, v117
	v_and_b32_e32 v118, 0xffffff80, v118
	v_and_b32_e32 v119, 0xffffff80, v119
	v_and_b32_e32 v120, 0xffffff80, v120
	v_and_b32_e32 v121, 0xffffff80, v121
	v_and_b32_e32 v122, 0xffffff80, v122
	v_and_b32_e32 v123, 0xffffff80, v123
	v_and_b32_e32 v124, 0xffffff80, v124
	v_and_b32_e32 v125, 0xffffff80, v125
	v_and_b32_e32 v126, 0xffffff80, v126
	v_and_b32_e32 v127, 0xffffff80, v127
	v_and_b32_e32 v128, 0xffffff80, v128
	v_and_b32_e32 v129, 0xffffff80, v129
	v_or3_b32 v114, v2, v114, 48
	v_or3_b32 v115, v2, v115, 49
	v_or3_b32 v116, v2, v116, 50
	v_or3_b32 v117, v2, v117, 51
	v_or3_b32 v118, v2, v118, 52
	v_or3_b32 v119, v2, v119, 53
	v_or3_b32 v120, v2, v120, 54
	v_or3_b32 v121, v2, v121, 55
	v_or3_b32 v122, v2, v122, 56
	v_or3_b32 v123, v2, v123, 57
	v_or3_b32 v124, v2, v124, 58
	v_or3_b32 v125, v2, v125, 59
	v_or3_b32 v126, v2, v126, 60
	v_or3_b32 v127, v2, v127, 61
	v_or3_b32 v128, v2, v128, 62
	v_or3_b32 v129, v2, v129, 63
	v_max_f32_e32 v130, v66, v67
	v_min_f32_e32 v131, v66, v67
	v_max_f32_e32 v132, v68, v69
	v_min_f32_e32 v133, v68, v69
	v_max_f32_e32 v134, v130, v132
	v_min_f32_e32 v135, v130, v132
	v_max_f32_e32 v136, v131, v133
	v_min_f32_e32 v137, v131, v133
	v_max_f32_e32 v138, v136, v135
	v_min_f32_e32 v139, v136, v135
	v_max_f32_e32 v140, v70, v71
	v_min_f32_e32 v141, v70, v71
	v_max_f32_e32 v142, v72, v73
	v_min_f32_e32 v143, v72, v73
	v_max_f32_e32 v144, v140, v142
	v_min_f32_e32 v145, v140, v142
	v_max_f32_e32 v146, v141, v143
	v_min_f32_e32 v147, v141, v143
	v_max_f32_e32 v148, v146, v145
	v_min_f32_e32 v149, v146, v145
	v_max_f32_e32 v150, v134, v144
	v_min_f32_e32 v151, v134, v144
	v_max_f32_e32 v152, v139, v149
	v_min_f32_e32 v153, v139, v149
	v_max_f32_e32 v154, v152, v151
	v_min_f32_e32 v155, v152, v151
	v_max_f32_e32 v156, v138, v148
	v_min_f32_e32 v157, v138, v148
	v_max_f32_e32 v158, v137, v147
	v_min_f32_e32 v159, v137, v147
	v_max_f32_e32 v160, v158, v157
	v_min_f32_e32 v161, v158, v157
	v_max_f32_e32 v162, v156, v154
	v_min_f32_e32 v163, v156, v154
	v_max_f32_e32 v164, v160, v155
	v_min_f32_e32 v165, v160, v155
	v_max_f32_e32 v166, v161, v153
	v_min_f32_e32 v167, v161, v153
	v_max_f32_e32 v168, v74, v75
	v_min_f32_e32 v169, v74, v75
	v_max_f32_e32 v170, v76, v77
	v_min_f32_e32 v171, v76, v77
	v_max_f32_e32 v172, v168, v170
	v_min_f32_e32 v173, v168, v170
	v_max_f32_e32 v174, v169, v171
	v_min_f32_e32 v34, v169, v171
	v_max_f32_e32 v35, v174, v173
	v_min_f32_e32 v36, v174, v173
	v_max_f32_e32 v37, v78, v79
	v_min_f32_e32 v38, v78, v79
	v_max_f32_e32 v39, v80, v81
	v_min_f32_e32 v40, v80, v81
	v_max_f32_e32 v41, v37, v39
	v_min_f32_e32 v42, v37, v39
	v_max_f32_e32 v43, v38, v40
	v_min_f32_e32 v44, v38, v40
	v_max_f32_e32 v45, v43, v42
	v_min_f32_e32 v46, v43, v42
	v_max_f32_e32 v47, v172, v41
	v_min_f32_e32 v48, v172, v41
	v_max_f32_e32 v49, v36, v46
	v_min_f32_e32 v50, v36, v46
	v_max_f32_e32 v51, v49, v48
	v_min_f32_e32 v54, v49, v48
	v_max_f32_e32 v55, v35, v45
	v_min_f32_e32 v56, v35, v45
	v_max_f32_e32 v57, v34, v44
	v_min_f32_e32 v58, v34, v44
	v_max_f32_e32 v59, v57, v56
	v_min_f32_e32 v60, v57, v56
	v_max_f32_e32 v61, v55, v51
	v_min_f32_e32 v62, v55, v51
	v_max_f32_e32 v63, v59, v54
	v_min_f32_e32 v66, v59, v54
	v_max_f32_e32 v67, v60, v50
	v_min_f32_e32 v68, v60, v50
	v_max_f32_e32 v69, v150, v47
	v_min_f32_e32 v130, v150, v47
	v_max_f32_e32 v132, v165, v66
	v_min_f32_e32 v131, v165, v66
	v_max_f32_e32 v133, v132, v130
	v_min_f32_e32 v136, v132, v130
	v_max_f32_e32 v135, v163, v62
	v_min_f32_e32 v70, v163, v62
	v_max_f32_e32 v71, v167, v68
	v_min_f32_e32 v72, v167, v68
	v_max_f32_e32 v73, v71, v70
	v_min_f32_e32 v140, v71, v70
	v_max_f32_e32 v142, v135, v133
	v_min_f32_e32 v141, v135, v133
	v_max_f32_e32 v143, v73, v136
	v_min_f32_e32 v146, v73, v136
	v_max_f32_e32 v145, v140, v131
	v_min_f32_e32 v134, v140, v131
	v_max_f32_e32 v144, v162, v61
	v_min_f32_e32 v139, v162, v61
	v_max_f32_e32 v149, v166, v67
	v_min_f32_e32 v152, v166, v67
	v_max_f32_e32 v151, v149, v139
	v_min_f32_e32 v138, v149, v139
	v_max_f32_e32 v148, v164, v63
	v_min_f32_e32 v137, v164, v63
	v_max_f32_e32 v147, v159, v58
	v_min_f32_e32 v158, v159, v58
	v_max_f32_e32 v157, v147, v137
	v_min_f32_e32 v156, v147, v137
	v_max_f32_e32 v154, v148, v151
	v_min_f32_e32 v160, v148, v151
	v_max_f32_e32 v155, v157, v138
	v_min_f32_e32 v161, v157, v138
	v_max_f32_e32 v153, v156, v152
	v_min_f32_e32 v74, v156, v152
	v_max_f32_e32 v75, v144, v142
	v_min_f32_e32 v76, v144, v142
	v_max_f32_e32 v77, v154, v141
	v_min_f32_e32 v168, v154, v141
	v_max_f32_e32 v170, v160, v143
	v_min_f32_e32 v169, v160, v143
	v_max_f32_e32 v171, v155, v146
	v_min_f32_e32 v174, v155, v146
	v_max_f32_e32 v173, v161, v145
	v_min_f32_e32 v78, v161, v145
	v_max_f32_e32 v79, v153, v134
	v_min_f32_e32 v80, v153, v134
	v_max_f32_e32 v81, v74, v72
	v_min_f32_e32 v37, v74, v72
	v_max_f32_e32 v39, v82, v83
	v_min_f32_e32 v38, v82, v83
	v_max_f32_e32 v40, v84, v85
	v_min_f32_e32 v43, v84, v85
	v_max_f32_e32 v42, v39, v40
	v_min_f32_e32 v172, v39, v40
	v_max_f32_e32 v41, v38, v43
	v_min_f32_e32 v36, v38, v43
	v_max_f32_e32 v46, v41, v172
	v_min_f32_e32 v49, v41, v172
	v_max_f32_e32 v48, v86, v87
	v_min_f32_e32 v35, v86, v87
	v_max_f32_e32 v45, v88, v89
	v_min_f32_e32 v34, v88, v89
	v_max_f32_e32 v44, v48, v45
	v_min_f32_e32 v57, v48, v45
	v_max_f32_e32 v56, v35, v34
	v_min_f32_e32 v55, v35, v34
	v_max_f32_e32 v51, v56, v57
	v_min_f32_e32 v59, v56, v57
	v_max_f32_e32 v54, v42, v44
	v_min_f32_e32 v60, v42, v44
	v_max_f32_e32 v50, v49, v59
; __device__ __forceinline__ void peer_topk_item(PREF P, int w, char* smem) {
;     ...
; #pragma unroll 4
;     for (int k = 0; k < 64; ++k) {
;       float x = __uint_as_float((__float_as_uint(src[k]) & ~127u) | (unsigned)(half * 64 + k));
;       ce_insert(top, x);
	v_min_f32_e32 v150, v49, v59
	v_max_f32_e32 v47, v50, v60
	v_min_f32_e32 v165, v50, v60
	v_max_f32_e32 v66, v46, v51
	v_min_f32_e32 v132, v46, v51
	v_max_f32_e32 v130, v36, v55
	v_min_f32_e32 v163, v36, v55
	v_max_f32_e32 v62, v130, v132
	v_min_f32_e32 v167, v130, v132
	v_max_f32_e32 v68, v66, v47
	v_min_f32_e32 v71, v66, v47
	v_max_f32_e32 v70, v62, v165
	v_min_f32_e32 v135, v62, v165
	v_max_f32_e32 v133, v167, v150
	v_min_f32_e32 v73, v167, v150
	v_max_f32_e32 v136, v90, v91
	v_min_f32_e32 v140, v90, v91
	v_max_f32_e32 v131, v92, v93
	v_min_f32_e32 v162, v92, v93
	v_max_f32_e32 v61, v136, v131
	v_min_f32_e32 v166, v136, v131
	v_max_f32_e32 v67, v140, v162
	v_min_f32_e32 v149, v140, v162
	v_max_f32_e32 v139, v67, v166
	v_min_f32_e32 v164, v67, v166
	v_max_f32_e32 v63, v94, v95
	v_min_f32_e32 v159, v94, v95
	v_max_f32_e32 v58, v96, v97
	v_min_f32_e32 v147, v96, v97
	v_max_f32_e32 v137, v63, v58
	v_min_f32_e32 v148, v63, v58
	v_max_f32_e32 v151, v159, v147
	v_min_f32_e32 v157, v159, v147
	v_max_f32_e32 v138, v151, v148
	v_min_f32_e32 v156, v151, v148
	v_max_f32_e32 v152, v61, v137
	v_min_f32_e32 v144, v61, v137
	v_max_f32_e32 v142, v164, v156
	v_min_f32_e32 v154, v164, v156
	v_max_f32_e32 v141, v142, v144
	v_min_f32_e32 v160, v142, v144
	v_max_f32_e32 v143, v139, v138
	v_min_f32_e32 v155, v139, v138
	v_max_f32_e32 v146, v149, v157
	v_min_f32_e32 v161, v149, v157
	v_max_f32_e32 v145, v146, v155
	v_min_f32_e32 v153, v146, v155
	v_max_f32_e32 v134, v143, v141
	v_min_f32_e32 v74, v143, v141
	v_max_f32_e32 v72, v145, v160
	v_min_f32_e32 v82, v145, v160
	v_max_f32_e32 v83, v153, v154
	v_min_f32_e32 v84, v153, v154
	v_max_f32_e32 v85, v54, v152
	v_min_f32_e32 v39, v54, v152
	v_max_f32_e32 v40, v135, v82
	v_min_f32_e32 v38, v135, v82
	v_max_f32_e32 v43, v40, v39
	v_min_f32_e32 v41, v40, v39
	v_max_f32_e32 v172, v71, v74
	v_min_f32_e32 v86, v71, v74
	v_max_f32_e32 v87, v73, v84
	v_min_f32_e32 v88, v73, v84
	v_max_f32_e32 v89, v87, v86
	v_min_f32_e32 v48, v87, v86
	v_max_f32_e32 v45, v172, v43
	v_min_f32_e32 v35, v172, v43
	v_max_f32_e32 v34, v89, v41
	v_min_f32_e32 v56, v89, v41
	v_max_f32_e32 v57, v48, v38
	v_min_f32_e32 v42, v48, v38
	v_max_f32_e32 v44, v68, v134
	v_min_f32_e32 v49, v68, v134
	v_max_f32_e32 v59, v133, v83
	v_min_f32_e32 v50, v133, v83
	v_max_f32_e32 v60, v59, v49
	v_min_f32_e32 v46, v59, v49
	v_max_f32_e32 v51, v70, v72
	v_min_f32_e32 v36, v70, v72
	v_max_f32_e32 v55, v163, v161
	v_min_f32_e32 v130, v163, v161
	v_max_f32_e32 v132, v55, v36
	v_min_f32_e32 v66, v55, v36
	v_max_f32_e32 v47, v51, v60
	v_min_f32_e32 v62, v51, v60
	v_max_f32_e32 v165, v132, v46
	v_min_f32_e32 v167, v132, v46
	v_max_f32_e32 v150, v66, v50
	v_min_f32_e32 v90, v66, v50
	v_max_f32_e32 v91, v44, v45
	v_min_f32_e32 v92, v44, v45
	v_max_f32_e32 v93, v47, v35
	v_min_f32_e32 v136, v47, v35
	v_max_f32_e32 v131, v62, v34
	v_min_f32_e32 v140, v62, v34
	v_max_f32_e32 v162, v165, v56
	v_min_f32_e32 v67, v165, v56
	v_max_f32_e32 v166, v167, v57
	v_min_f32_e32 v94, v167, v57
	v_max_f32_e32 v95, v150, v42
	v_min_f32_e32 v96, v150, v42
	v_max_f32_e32 v97, v90, v88
	v_min_f32_e32 v63, v90, v88
	v_max_f32_e32 v58, v98, v99
	v_min_f32_e32 v159, v98, v99
	v_max_f32_e32 v147, v100, v101
	v_min_f32_e32 v151, v100, v101
	v_max_f32_e32 v148, v58, v147
	v_min_f32_e32 v61, v58, v147
	v_max_f32_e32 v137, v159, v151
	v_min_f32_e32 v164, v159, v151
	v_max_f32_e32 v156, v137, v61
	v_min_f32_e32 v142, v137, v61
	v_max_f32_e32 v144, v102, v103
	v_min_f32_e32 v139, v102, v103
	v_max_f32_e32 v138, v104, v105
	v_min_f32_e32 v149, v104, v105
	v_max_f32_e32 v157, v144, v138
	v_min_f32_e32 v146, v144, v138
	v_max_f32_e32 v155, v139, v149
	v_min_f32_e32 v143, v139, v149
	v_max_f32_e32 v141, v155, v146
	v_min_f32_e32 v145, v155, v146
	v_max_f32_e32 v160, v148, v157
	v_min_f32_e32 v153, v148, v157
	v_max_f32_e32 v154, v142, v145
	v_min_f32_e32 v54, v142, v145
	v_max_f32_e32 v152, v154, v153
	v_min_f32_e32 v135, v154, v153
	v_max_f32_e32 v82, v156, v141
	v_min_f32_e32 v40, v156, v141
	v_max_f32_e32 v39, v164, v143
	v_min_f32_e32 v71, v164, v143
	v_max_f32_e32 v74, v39, v40
	v_min_f32_e32 v73, v39, v40
	v_max_f32_e32 v84, v82, v152
	v_min_f32_e32 v87, v82, v152
	v_max_f32_e32 v86, v74, v135
	v_min_f32_e32 v172, v74, v135
	v_max_f32_e32 v43, v73, v54
	v_min_f32_e32 v89, v73, v54
	v_max_f32_e32 v41, v106, v107
	v_min_f32_e32 v48, v106, v107
	v_max_f32_e32 v38, v108, v109
	v_min_f32_e32 v68, v108, v109
	v_max_f32_e32 v134, v41, v38
	v_min_f32_e32 v133, v41, v38
	v_max_f32_e32 v83, v48, v68
	v_min_f32_e32 v59, v48, v68
	v_max_f32_e32 v49, v83, v133
	v_min_f32_e32 v70, v83, v133
	v_max_f32_e32 v72, v110, v111
	v_min_f32_e32 v163, v110, v111
	v_max_f32_e32 v161, v112, v113
	v_min_f32_e32 v55, v112, v113
	v_max_f32_e32 v36, v72, v161
	v_min_f32_e32 v51, v72, v161
	v_max_f32_e32 v60, v163, v55
	v_min_f32_e32 v132, v163, v55
	v_max_f32_e32 v46, v60, v51
	v_min_f32_e32 v66, v60, v51
	v_max_f32_e32 v50, v134, v36
	v_min_f32_e32 v44, v134, v36
	v_max_f32_e32 v45, v70, v66
	v_min_f32_e32 v47, v70, v66
	v_max_f32_e32 v35, v45, v44
	v_min_f32_e32 v62, v45, v44
	v_max_f32_e32 v34, v49, v46
	v_min_f32_e32 v165, v49, v46
	v_max_f32_e32 v56, v59, v132
	v_min_f32_e32 v167, v59, v132
	v_max_f32_e32 v57, v56, v165
	v_min_f32_e32 v150, v56, v165
	v_max_f32_e32 v42, v34, v35
	v_min_f32_e32 v90, v34, v35
	v_max_f32_e32 v88, v57, v62
	v_min_f32_e32 v98, v57, v62
	v_max_f32_e32 v99, v150, v47
	v_min_f32_e32 v100, v150, v47
	v_max_f32_e32 v101, v160, v50
	v_min_f32_e32 v58, v160, v50
	v_max_f32_e32 v147, v172, v98
	v_min_f32_e32 v159, v172, v98
	v_max_f32_e32 v151, v147, v58
	v_min_f32_e32 v137, v147, v58
; __device__ __forceinline__ void peer_topk_item(PREF P, int w, char* smem) {
;     ...
; #pragma unroll 4
;     for (int k = 0; k < 64; ++k) {
;       float x = __uint_as_float((__float_as_uint(src[k]) & ~127u) | (unsigned)(half * 64 + k));
;       ce_insert(top, x);
	v_max_f32_e32 v61, v87, v90
	v_min_f32_e32 v102, v87, v90
	v_max_f32_e32 v103, v89, v100
	v_min_f32_e32 v104, v89, v100
	v_max_f32_e32 v105, v103, v102
	v_min_f32_e32 v144, v103, v102
	v_max_f32_e32 v138, v61, v151
	v_min_f32_e32 v139, v61, v151
	v_max_f32_e32 v149, v105, v137
	v_min_f32_e32 v155, v105, v137
	v_max_f32_e32 v146, v144, v159
	v_min_f32_e32 v148, v144, v159
	v_max_f32_e32 v157, v84, v42
	v_min_f32_e32 v142, v84, v42
	v_max_f32_e32 v145, v43, v99
	v_min_f32_e32 v154, v43, v99
	v_max_f32_e32 v153, v145, v142
	v_min_f32_e32 v156, v145, v142
	v_max_f32_e32 v141, v86, v88
	v_min_f32_e32 v164, v86, v88
	v_max_f32_e32 v143, v71, v167
	v_min_f32_e32 v39, v71, v167
	v_max_f32_e32 v40, v143, v164
	v_min_f32_e32 v82, v143, v164
	v_max_f32_e32 v152, v141, v153
	v_min_f32_e32 v74, v141, v153
	v_max_f32_e32 v135, v40, v156
	v_min_f32_e32 v73, v40, v156
	v_max_f32_e32 v54, v82, v154
	v_min_f32_e32 v106, v82, v154
	v_max_f32_e32 v107, v157, v138
	v_min_f32_e32 v108, v157, v138
	v_max_f32_e32 v109, v152, v139
	v_min_f32_e32 v41, v152, v139
	v_max_f32_e32 v38, v74, v149
	v_min_f32_e32 v48, v74, v149
	v_max_f32_e32 v68, v135, v155
	v_min_f32_e32 v83, v135, v155
	v_max_f32_e32 v133, v73, v146
	v_min_f32_e32 v110, v73, v146
	v_max_f32_e32 v111, v54, v148
	v_min_f32_e32 v112, v54, v148
	v_max_f32_e32 v113, v106, v104
	v_min_f32_e32 v72, v106, v104
	v_max_f32_e32 v161, v114, v115
	v_min_f32_e32 v163, v114, v115
	v_max_f32_e32 v55, v116, v117
	v_min_f32_e32 v60, v116, v117
	v_max_f32_e32 v51, v161, v55
	v_min_f32_e32 v134, v161, v55
	v_max_f32_e32 v36, v163, v60
	v_min_f32_e32 v70, v163, v60
	v_max_f32_e32 v66, v36, v134
	v_min_f32_e32 v45, v36, v134
	v_max_f32_e32 v44, v118, v119
	v_min_f32_e32 v49, v118, v119
	v_max_f32_e32 v46, v120, v121
	v_min_f32_e32 v59, v120, v121
	v_max_f32_e32 v132, v44, v46
	v_min_f32_e32 v56, v44, v46
	v_max_f32_e32 v165, v49, v59
	v_min_f32_e32 v34, v49, v59
	v_max_f32_e32 v35, v165, v56
	v_min_f32_e32 v57, v165, v56
	v_max_f32_e32 v62, v51, v132
	v_min_f32_e32 v150, v51, v132
	v_max_f32_e32 v47, v45, v57
	v_min_f32_e32 v160, v45, v57
	v_max_f32_e32 v50, v47, v150
	v_min_f32_e32 v172, v47, v150
	v_max_f32_e32 v98, v66, v35
	v_min_f32_e32 v147, v66, v35
	v_max_f32_e32 v58, v70, v34
	v_min_f32_e32 v87, v70, v34
	v_max_f32_e32 v90, v58, v147
	v_min_f32_e32 v89, v58, v147
	v_max_f32_e32 v100, v98, v50
	v_min_f32_e32 v103, v98, v50
	v_max_f32_e32 v102, v90, v172
	v_min_f32_e32 v61, v90, v172
	v_max_f32_e32 v151, v89, v160
	v_min_f32_e32 v105, v89, v160
	v_max_f32_e32 v137, v122, v123
	v_min_f32_e32 v144, v122, v123
	v_max_f32_e32 v159, v124, v125
	v_min_f32_e32 v84, v124, v125
	v_max_f32_e32 v42, v137, v159
	v_min_f32_e32 v43, v137, v159
	v_max_f32_e32 v99, v144, v84
	v_min_f32_e32 v145, v144, v84
	v_max_f32_e32 v142, v99, v43
	v_min_f32_e32 v86, v99, v43
	v_max_f32_e32 v88, v126, v127
	v_min_f32_e32 v71, v126, v127
	v_max_f32_e32 v167, v128, v129
	v_min_f32_e32 v143, v128, v129
	v_max_f32_e32 v164, v88, v167
	v_min_f32_e32 v141, v88, v167
	v_max_f32_e32 v153, v71, v143
	v_min_f32_e32 v40, v71, v143
	v_max_f32_e32 v156, v153, v141
	v_min_f32_e32 v82, v153, v141
	v_max_f32_e32 v154, v42, v164
	v_min_f32_e32 v157, v42, v164
	v_max_f32_e32 v138, v86, v82
	v_min_f32_e32 v152, v86, v82
	v_max_f32_e32 v139, v138, v157
	v_min_f32_e32 v74, v138, v157
	v_max_f32_e32 v149, v142, v156
	v_min_f32_e32 v135, v142, v156
	v_max_f32_e32 v155, v145, v40
	v_min_f32_e32 v73, v145, v40
	v_max_f32_e32 v146, v155, v135
	v_min_f32_e32 v54, v155, v135
	v_max_f32_e32 v148, v149, v139
	v_min_f32_e32 v106, v149, v139
	v_max_f32_e32 v104, v146, v74
	v_min_f32_e32 v114, v146, v74
	v_max_f32_e32 v115, v54, v152
	v_min_f32_e32 v116, v54, v152
	v_max_f32_e32 v117, v62, v154
	v_min_f32_e32 v161, v62, v154
	v_max_f32_e32 v55, v61, v114
	v_min_f32_e32 v163, v61, v114
	v_max_f32_e32 v60, v55, v161
	v_min_f32_e32 v36, v55, v161
	v_max_f32_e32 v134, v103, v106
	v_min_f32_e32 v118, v103, v106
	v_max_f32_e32 v119, v105, v116
	v_min_f32_e32 v120, v105, v116
	v_max_f32_e32 v121, v119, v118
	v_min_f32_e32 v44, v119, v118
	v_max_f32_e32 v46, v134, v60
	v_min_f32_e32 v49, v134, v60
	v_max_f32_e32 v59, v121, v36
	v_min_f32_e32 v165, v121, v36
	v_max_f32_e32 v56, v44, v163
	v_min_f32_e32 v51, v44, v163
	v_max_f32_e32 v132, v100, v148
	v_min_f32_e32 v45, v100, v148
	v_max_f32_e32 v57, v151, v115
	v_min_f32_e32 v47, v151, v115
	v_max_f32_e32 v150, v57, v45
	v_min_f32_e32 v66, v57, v45
	v_max_f32_e32 v35, v102, v104
	v_min_f32_e32 v70, v102, v104
	v_max_f32_e32 v34, v87, v73
	v_min_f32_e32 v58, v87, v73
	v_max_f32_e32 v147, v34, v70
	v_min_f32_e32 v98, v34, v70
	v_max_f32_e32 v50, v35, v150
	v_min_f32_e32 v90, v35, v150
	v_max_f32_e32 v172, v147, v66
	v_min_f32_e32 v89, v147, v66
	v_max_f32_e32 v160, v98, v47
	v_min_f32_e32 v122, v98, v47
	v_max_f32_e32 v123, v132, v46
	v_min_f32_e32 v124, v132, v46
	v_max_f32_e32 v125, v50, v49
	v_min_f32_e32 v137, v50, v49
	v_max_f32_e32 v159, v90, v59
	v_min_f32_e32 v144, v90, v59
	v_max_f32_e32 v84, v172, v165
	v_min_f32_e32 v99, v172, v165
	v_max_f32_e32 v43, v89, v56
	v_min_f32_e32 v126, v89, v56
	v_max_f32_e32 v127, v160, v51
	v_min_f32_e32 v128, v160, v51
	v_max_f32_e32 v129, v122, v120
	v_min_f32_e32 v88, v122, v120
	v_max_f32_e32 v167, v69, v130
	v_max_f32_e32 v71, v75, v63
	v_max_f32_e32 v143, v76, v97
	v_max_f32_e32 v153, v77, v96
	v_max_f32_e32 v141, v168, v95
	v_max_f32_e32 v42, v170, v94
	v_max_f32_e32 v164, v169, v166
	v_max_f32_e32 v86, v171, v67
	v_max_f32_e32 v82, v174, v162
	v_max_f32_e32 v138, v173, v140
	v_max_f32_e32 v157, v78, v131
	v_max_f32_e32 v142, v79, v136
	v_max_f32_e32 v156, v80, v93
	v_max_f32_e32 v145, v81, v92
; __device__ __forceinline__ void peer_topk_item(PREF P, int w, char* smem) {
;     ...
; #pragma unroll 4
;     for (int k = 0; k < 64; ++k) {
;       float x = __uint_as_float((__float_as_uint(src[k]) & ~127u) | (unsigned)(half * 64 + k));
;       ce_insert(top, x);
	v_max_f32_e32 v40, v37, v91
	v_max_f32_e32 v155, v158, v85
	v_max_f32_e32 v135, v167, v82
	v_min_f32_e32 v149, v167, v82
	v_max_f32_e32 v139, v71, v138
	v_min_f32_e32 v146, v71, v138
	v_max_f32_e32 v74, v143, v157
	v_min_f32_e32 v54, v143, v157
	v_max_f32_e32 v152, v153, v142
	v_min_f32_e32 v62, v153, v142
	v_max_f32_e32 v154, v141, v156
	v_min_f32_e32 v61, v141, v156
	v_max_f32_e32 v114, v42, v145
	v_min_f32_e32 v55, v42, v145
	v_max_f32_e32 v161, v164, v40
	v_min_f32_e32 v103, v164, v40
	v_max_f32_e32 v106, v86, v155
	v_min_f32_e32 v105, v86, v155
	v_max_f32_e32 v116, v135, v154
	v_min_f32_e32 v119, v135, v154
	v_max_f32_e32 v118, v139, v114
	v_min_f32_e32 v134, v139, v114
	v_max_f32_e32 v60, v74, v161
	v_min_f32_e32 v121, v74, v161
	v_max_f32_e32 v36, v152, v106
	v_min_f32_e32 v44, v152, v106
	v_max_f32_e32 v163, v149, v61
	v_min_f32_e32 v100, v149, v61
	v_max_f32_e32 v148, v146, v55
	v_min_f32_e32 v151, v146, v55
	v_max_f32_e32 v115, v54, v103
	v_min_f32_e32 v57, v54, v103
	v_max_f32_e32 v45, v62, v105
	v_min_f32_e32 v102, v62, v105
	v_max_f32_e32 v104, v116, v60
	v_min_f32_e32 v87, v116, v60
	v_max_f32_e32 v73, v118, v36
	v_min_f32_e32 v34, v118, v36
	v_max_f32_e32 v70, v119, v121
	v_min_f32_e32 v35, v119, v121
	v_max_f32_e32 v150, v134, v44
	v_min_f32_e32 v147, v134, v44
	v_max_f32_e32 v66, v163, v115
	v_min_f32_e32 v98, v163, v115
	v_max_f32_e32 v47, v148, v45
	v_min_f32_e32 v132, v148, v45
	v_max_f32_e32 v46, v100, v57
	v_min_f32_e32 v50, v100, v57
	v_max_f32_e32 v49, v151, v102
	v_min_f32_e32 v90, v151, v102
	v_max_f32_e32 v59, v104, v73
	v_min_f32_e32 v172, v104, v73
	v_max_f32_e32 v165, v87, v34
	v_min_f32_e32 v89, v87, v34
	v_max_f32_e32 v56, v70, v150
	v_min_f32_e32 v160, v70, v150
	v_max_f32_e32 v51, v35, v147
	v_min_f32_e32 v122, v35, v147
	v_max_f32_e32 v120, v66, v47
	v_min_f32_e32 v69, v66, v47
	v_max_f32_e32 v130, v98, v132
	v_min_f32_e32 v75, v98, v132
	v_max_f32_e32 v63, v46, v49
	v_min_f32_e32 v76, v46, v49
	v_max_f32_e32 v97, v50, v90
	v_min_f32_e32 v77, v50, v90
	v_max_f32_e32 v96, v101, v58
	v_max_f32_e32 v168, v107, v88
	v_max_f32_e32 v95, v108, v129
	v_max_f32_e32 v170, v109, v128
	v_max_f32_e32 v94, v41, v127
	v_max_f32_e32 v169, v38, v126
	v_max_f32_e32 v166, v48, v43
	v_max_f32_e32 v171, v68, v99
	v_max_f32_e32 v67, v83, v84
	v_max_f32_e32 v174, v133, v144
	v_max_f32_e32 v162, v110, v159
	v_max_f32_e32 v173, v111, v137
	v_max_f32_e32 v140, v112, v125
	v_max_f32_e32 v78, v113, v124
	v_max_f32_e32 v131, v72, v123
	v_max_f32_e32 v79, v39, v117
	v_max_f32_e32 v136, v96, v67
	v_min_f32_e32 v80, v96, v67
	v_max_f32_e32 v93, v168, v174
	v_min_f32_e32 v81, v168, v174
	v_max_f32_e32 v92, v95, v162
	v_min_f32_e32 v37, v95, v162
	v_max_f32_e32 v91, v170, v173
	v_min_f32_e32 v158, v170, v173
	v_max_f32_e32 v85, v94, v140
	v_min_f32_e32 v167, v94, v140
	v_max_f32_e32 v82, v169, v78
	v_min_f32_e32 v71, v169, v78
	v_max_f32_e32 v138, v166, v131
	v_min_f32_e32 v143, v166, v131
	v_max_f32_e32 v157, v171, v79
	v_min_f32_e32 v153, v171, v79
	v_max_f32_e32 v142, v136, v85
	v_min_f32_e32 v141, v136, v85
	v_max_f32_e32 v156, v93, v82
	v_min_f32_e32 v42, v93, v82
	v_max_f32_e32 v145, v92, v138
	v_min_f32_e32 v164, v92, v138
	v_max_f32_e32 v40, v91, v157
	v_min_f32_e32 v86, v91, v157
	v_max_f32_e32 v155, v80, v167
	v_min_f32_e32 v135, v80, v167
	v_max_f32_e32 v154, v81, v71
	v_min_f32_e32 v139, v81, v71
	v_max_f32_e32 v114, v37, v143
	v_min_f32_e32 v74, v37, v143
	v_max_f32_e32 v161, v158, v153
	v_min_f32_e32 v152, v158, v153
	v_max_f32_e32 v106, v142, v145
	v_min_f32_e32 v149, v142, v145
	v_max_f32_e32 v61, v156, v40
	v_min_f32_e32 v146, v156, v40
	v_max_f32_e32 v55, v141, v164
	v_min_f32_e32 v54, v141, v164
	v_max_f32_e32 v103, v42, v86
	v_min_f32_e32 v62, v42, v86
	v_max_f32_e32 v105, v155, v114
	v_min_f32_e32 v116, v155, v114
	v_max_f32_e32 v60, v154, v161
	v_min_f32_e32 v118, v154, v161
	v_max_f32_e32 v36, v135, v74
	v_min_f32_e32 v119, v135, v74
	v_max_f32_e32 v121, v139, v152
	v_min_f32_e32 v134, v139, v152
	v_max_f32_e32 v44, v106, v61
	v_min_f32_e32 v163, v106, v61
	v_max_f32_e32 v115, v149, v146
	v_min_f32_e32 v148, v149, v146
	v_max_f32_e32 v45, v55, v103
	v_min_f32_e32 v100, v55, v103
	v_max_f32_e32 v57, v54, v62
	v_min_f32_e32 v151, v54, v62
	v_max_f32_e32 v102, v105, v60
	v_min_f32_e32 v104, v105, v60
	v_max_f32_e32 v73, v116, v118
	v_min_f32_e32 v87, v116, v118
	v_max_f32_e32 v34, v36, v121
	v_min_f32_e32 v70, v36, v121
	v_max_f32_e32 v150, v119, v134
	v_min_f32_e32 v35, v119, v134
	v_max_f32_e32 v147, v59, v35
	v_max_f32_e32 v66, v172, v150
	v_max_f32_e32 v47, v165, v70
	v_max_f32_e32 v98, v89, v34
	v_max_f32_e32 v132, v56, v87
	v_max_f32_e32 v46, v160, v73
	v_max_f32_e32 v49, v51, v104
	v_max_f32_e32 v50, v122, v102
	v_max_f32_e32 v90, v120, v151
	v_max_f32_e32 v101, v69, v57
	v_max_f32_e32 v58, v130, v100
	v_max_f32_e32 v107, v75, v45
	v_max_f32_e32 v88, v63, v148
	v_max_f32_e32 v108, v76, v115
	v_max_f32_e32 v129, v97, v163
	v_max_f32_e32 v109, v77, v44
	v_max_f32_e32 v128, v147, v90
	v_min_f32_e32 v41, v147, v90
	v_max_f32_e32 v127, v66, v101
	v_min_f32_e32 v38, v66, v101
	v_max_f32_e32 v126, v47, v58
	v_min_f32_e32 v48, v47, v58
	v_max_f32_e32 v43, v98, v107
	v_min_f32_e32 v68, v98, v107
; __device__ __forceinline__ void peer_topk_item(PREF P, int w, char* smem) {
;     ...
;       ce_insert(top, x);
;     }
;     if (half == 1) {
; #pragma unroll
;       for (int k = 0; k < 16; ++k) Ll[row * 17 + k] = top[k];
;     }
;     __syncthreads();
;     if (half == 0) {
; #pragma unroll
;       for (int k = 0; k < 16; ++k) ce_insert(top, Ll[row * 17 + k]);
;     }
	v_max_f32_e32 v99, v132, v88
	v_min_f32_e32 v83, v132, v88
	v_max_f32_e32 v84, v46, v108
	v_min_f32_e32 v133, v46, v108
	v_max_f32_e32 v144, v49, v129
	v_min_f32_e32 v110, v49, v129
	v_max_f32_e32 v159, v50, v109
	v_min_f32_e32 v111, v50, v109
	v_max_f32_e32 v137, v128, v99
	v_min_f32_e32 v112, v128, v99
	v_max_f32_e32 v125, v127, v84
	v_min_f32_e32 v113, v127, v84
	v_max_f32_e32 v124, v126, v144
	v_min_f32_e32 v72, v126, v144
	v_max_f32_e32 v123, v43, v159
	v_min_f32_e32 v39, v43, v159
	v_max_f32_e32 v117, v41, v83
	v_min_f32_e32 v96, v41, v83
	v_max_f32_e32 v67, v38, v133
	v_min_f32_e32 v168, v38, v133
	v_max_f32_e32 v174, v48, v110
	v_min_f32_e32 v95, v48, v110
	v_max_f32_e32 v162, v68, v111
	v_min_f32_e32 v170, v68, v111
	v_max_f32_e32 v173, v137, v124
	v_min_f32_e32 v94, v137, v124
	v_max_f32_e32 v140, v125, v123
	v_min_f32_e32 v169, v125, v123
	v_max_f32_e32 v78, v112, v72
	v_min_f32_e32 v166, v112, v72
	v_max_f32_e32 v131, v113, v39
	v_min_f32_e32 v171, v113, v39
	v_max_f32_e32 v79, v117, v174
	v_min_f32_e32 v136, v117, v174
	v_max_f32_e32 v85, v67, v162
	v_min_f32_e32 v93, v67, v162
	v_max_f32_e32 v82, v96, v95
	v_min_f32_e32 v92, v96, v95
	v_max_f32_e32 v138, v168, v170
	v_min_f32_e32 v91, v168, v170
	v_max_f32_e32 v19, v173, v140
	v_min_f32_e32 v18, v173, v140
	v_max_f32_e32 v17, v94, v169
	v_min_f32_e32 v16, v94, v169
	v_max_f32_e32 v15, v78, v131
	v_min_f32_e32 v14, v78, v131
	v_max_f32_e32 v13, v166, v171
	v_min_f32_e32 v12, v166, v171
	v_max_f32_e32 v11, v79, v85
	v_min_f32_e32 v10, v79, v85
	v_max_f32_e32 v9, v136, v93
	v_min_f32_e32 v8, v136, v93
	v_max_f32_e32 v7, v82, v138
	v_min_f32_e32 v6, v82, v138
	v_max_f32_e32 v5, v92, v91
	v_min_f32_e32 v4, v92, v91
	s_movk_i32 s4, 0x44
	v_cmp_eq_u32_e32 vcc, 1, v1
	v_mad_u32_u24 v2, v0, s4, v220
	s_and_saveexec_b64 s[4:5], vcc
	s_cbranch_execz .LBB0_631
	ds_write2_b32 v2, v19, v18 offset1:1
	ds_write2_b32 v2, v17, v16 offset0:2 offset1:3
	ds_write2_b32 v2, v15, v14 offset0:4 offset1:5
	ds_write2_b32 v2, v13, v12 offset0:6 offset1:7
	ds_write2_b32 v2, v11, v10 offset0:8 offset1:9
	ds_write2_b32 v2, v9, v8 offset0:10 offset1:11
	ds_write2_b32 v2, v7, v6 offset0:12 offset1:13
	ds_write2_b32 v2, v5, v4 offset0:14 offset1:15
.LBB0_631:
	s_or_b64 exec, exec, s[4:5]
	s_movk_i32 s4, 0x80
	v_cmp_gt_u32_e32 vcc, s4, v53
	s_waitcnt lgkmcnt(0)
	s_barrier
	s_and_saveexec_b64 s[4:5], vcc
	s_cbranch_execz .LBB0_633
	ds_read2_b32 v[66:67], v2 offset0:0 offset1:1
	ds_read2_b32 v[68:69], v2 offset0:2 offset1:3
	ds_read2_b32 v[70:71], v2 offset0:4 offset1:5
	ds_read2_b32 v[72:73], v2 offset0:6 offset1:7
	ds_read2_b32 v[74:75], v2 offset0:8 offset1:9
	ds_read2_b32 v[76:77], v2 offset0:10 offset1:11
	ds_read2_b32 v[78:79], v2 offset0:12 offset1:13
	ds_read2_b32 v[80:81], v2 offset0:14 offset1:15
	s_waitcnt lgkmcnt(0)
	v_max_f32_e32 v82, v19, v81
	v_max_f32_e32 v83, v18, v80
	v_max_f32_e32 v84, v17, v79
	v_max_f32_e32 v85, v16, v78
	v_max_f32_e32 v86, v15, v77
	v_max_f32_e32 v87, v14, v76
	v_max_f32_e32 v88, v13, v75
	v_max_f32_e32 v89, v12, v74
	v_max_f32_e32 v90, v11, v73
	v_max_f32_e32 v91, v10, v72
	v_max_f32_e32 v92, v9, v71
	v_max_f32_e32 v93, v8, v70
	v_max_f32_e32 v94, v7, v69
	v_max_f32_e32 v95, v6, v68
	v_max_f32_e32 v96, v5, v67
	v_max_f32_e32 v97, v4, v66
	v_max_f32_e32 v98, v82, v90
	v_min_f32_e32 v99, v82, v90
	v_max_f32_e32 v100, v83, v91
	v_min_f32_e32 v101, v83, v91
	v_max_f32_e32 v102, v84, v92
	v_min_f32_e32 v103, v84, v92
	v_max_f32_e32 v104, v85, v93
	v_min_f32_e32 v105, v85, v93
	v_max_f32_e32 v106, v86, v94
	v_min_f32_e32 v107, v86, v94
	v_max_f32_e32 v108, v87, v95
	v_min_f32_e32 v109, v87, v95
	v_max_f32_e32 v110, v88, v96
	v_min_f32_e32 v111, v88, v96
	v_max_f32_e32 v112, v89, v97
	v_min_f32_e32 v113, v89, v97
	v_max_f32_e32 v114, v98, v106
	v_min_f32_e32 v115, v98, v106
	v_max_f32_e32 v116, v100, v108
	v_min_f32_e32 v117, v100, v108
	v_max_f32_e32 v118, v102, v110
	v_min_f32_e32 v119, v102, v110
	v_max_f32_e32 v120, v104, v112
	v_min_f32_e32 v121, v104, v112
	v_max_f32_e32 v122, v99, v107
	v_min_f32_e32 v123, v99, v107
	v_max_f32_e32 v124, v101, v109
	v_min_f32_e32 v125, v101, v109
	v_max_f32_e32 v126, v103, v111
	v_min_f32_e32 v127, v103, v111
	v_max_f32_e32 v128, v105, v113
	v_min_f32_e32 v129, v105, v113
	v_max_f32_e32 v82, v114, v118
	v_min_f32_e32 v90, v114, v118
	v_max_f32_e32 v83, v116, v120
	v_min_f32_e32 v91, v116, v120
	v_max_f32_e32 v84, v115, v119
	v_min_f32_e32 v92, v115, v119
	v_max_f32_e32 v85, v117, v121
	v_min_f32_e32 v93, v117, v121
	v_max_f32_e32 v86, v122, v126
	v_min_f32_e32 v94, v122, v126
	v_max_f32_e32 v87, v124, v128
	v_min_f32_e32 v95, v124, v128
	v_max_f32_e32 v88, v123, v127
	v_min_f32_e32 v96, v123, v127
	v_max_f32_e32 v89, v125, v129
	v_min_f32_e32 v97, v125, v129
	v_max_f32_e32 v19, v82, v83
	v_min_f32_e32 v18, v82, v83
	v_max_f32_e32 v17, v90, v91
	v_min_f32_e32 v16, v90, v91
	v_max_f32_e32 v15, v84, v85
	v_min_f32_e32 v14, v84, v85
	v_max_f32_e32 v13, v92, v93
	v_min_f32_e32 v12, v92, v93
	v_max_f32_e32 v11, v86, v87
	v_min_f32_e32 v10, v86, v87
	v_max_f32_e32 v9, v94, v95
	v_min_f32_e32 v8, v94, v95
	v_max_f32_e32 v7, v88, v89
	v_min_f32_e32 v6, v88, v89
	v_max_f32_e32 v5, v96, v97
	v_min_f32_e32 v4, v96, v97
